# FFN-up epilogue: row statistics of the first four row groups prefetched at the unit-loop header (before the K-loop) so the epilogue starts without a load round trip
# speedup vs baseline: 1.0029x; 1.0029x over previous
; #define G opaque_s(G0)
;     __host__ __device__ bool next(int i, Unit& u) const {
;         const long L = (long)i * G + c; if (L >= nwg) return false;
;         int wgid = (int)L; { const int q = nwg / NXCD, r = nwg % NXCD, xcd = wgid % NXCD, off = wgid / NXCD; wgid = (xcd < r ? xcd * (q + 1) : r * (q + 1) + (xcd - r) * q) + off; }
;         const int nig = WGM * nN, gid = wgid / nig, fm = gid * WGM, gsz = (nM - fm) < WGM ? (nM - fm) : WGM;
;         u.pm = fm + ((wgid % nig) % gsz); u.pn = (wgid % nig) / gsz; return true;
;     __device__ __forceinline__ void operator()(const f32x4 (&acc)[2][2][4][2], const Unit& u, int wr, int wc, int fr, int fq) const {
;     ...
;             for (int m = 0; m < 4; ++m) { if (m == 0) asm volatile("" ::: "memory"); const int row = row0 + ai * HALF + m * 16; const float rs = rstd_of(ssq, row);
.LBB0_115:
	v_lshl_add_u32 v252, s0, 8, v140
	v_ashrrev_i32_e32 v253, 31, v252
	v_lshl_add_u64 v[252:253], v[252:253], 4, s[18:19]
	global_load_dwordx4 v[222:225], v[252:253], off
	global_load_dwordx4 v[226:229], v[252:253], off offset:256
	global_load_dwordx4 v[244:247], v[252:253], off offset:512
	global_load_dwordx4 v[248:251], v[252:253], off offset:768
	s_add_i32 s45, s45, 1
	s_mul_i32 s6, s45, s44
	s_mul_hi_u32 s7, s45, s12
	s_add_i32 s7, s7, s6
	s_mul_i32 s6, s45, s12
	s_add_u32 s8, s6, s13
	s_addc_u32 s9, s7, s35
	v_cmp_gt_i64_e32 vcc, s[8:9], v[242:243]
	v_cmp_lt_i64_e64 s[6:7], s[8:9], v[232:233]
	s_cbranch_vccnz .LBB0_117
	s_ashr_i32 s9, s8, 31
	s_lshr_b32 s9, s9, 29
	s_add_i32 s9, s8, s9
	s_ashr_i32 s22, s9, 3
	s_and_b32 s9, s9, -8
	s_sub_i32 s8, s8, s9
	s_cmp_lt_i32 s8, 0
	s_cselect_b32 s9, s87, 0xb0
	s_mul_i32 s8, s8, s9
	s_add_i32 s8, s8, s22
	s_mul_hi_i32 s9, s8, 0x2e8ba2e9
	s_lshr_b32 s22, s9, 31
	s_ashr_i32 s9, s9, 5
	s_add_i32 s9, s9, s22
	s_lshl_b32 s23, s9, 3
	s_sub_i32 s22, 64, s23
	s_min_i32 s24, s22, 8
	s_abs_i32 s22, s24
	v_cvt_f32_u32_e32 v0, s22
	s_sub_i32 s26, 0, s22
	s_mulk_i32 s9, 0xb0
	s_sub_i32 s8, s8, s9
	v_rcp_iflag_f32_e32 v0, v0
	s_abs_i32 s9, s8
	s_xor_b32 s25, s8, s24
	s_ashr_i32 s25, s25, 31
	v_mul_f32_e32 v0, 0x4f7ffffe, v0
	v_cvt_u32_f32_e32 v0, v0
	s_nop 0
	v_readfirstlane_b32 s27, v0
	s_mul_i32 s26, s26, s27
	s_mul_hi_u32 s26, s27, s26
	s_add_i32 s27, s27, s26
	s_mul_hi_u32 s26, s9, s27
	s_mul_i32 s27, s26, s22
	s_sub_i32 s9, s9, s27
	s_add_i32 s28, s26, 1
	s_sub_i32 s27, s9, s22
	s_cmp_ge_u32 s9, s22
	s_cselect_b32 s26, s28, s26
	s_cselect_b32 s9, s27, s9
	s_add_i32 s27, s26, 1
	s_cmp_ge_u32 s9, s22
	s_cselect_b32 s9, s27, s26
	s_xor_b32 s9, s9, s25
	s_sub_i32 s22, s9, s25
	s_mul_i32 s9, s22, s24
	s_sub_i32 s8, s8, s9
	s_add_i32 s24, s23, s8

; __device__ __forceinline__ u32x4 pack8(const f32x4 a, const f32x4 b) { u32x4 w; w.x = cvt_pk_bf16(a[0], a[1]); w.y = cvt_pk_bf16(a[2], a[3]); w.z = cvt_pk_bf16(b[0], b[1]); w.w = cvt_pk_bf16(b[2], b[3]); return w; }
; __device__ __forceinline__ float rstd_of(const float* ssq, int row) { const f32x4 a = *(const f32x4*)(ssq + (size_t)row * 4);
;     return __builtin_amdgcn_rsqf(((a[0] + a[1]) + (a[2] + a[3])) * (1.0f / 1024.0f) + 1e-6f); }
; __device__ __forceinline__ float sigm(float g) { return __builtin_amdgcn_rcpf(1.0f + __builtin_amdgcn_exp2f(-1.4426950408889634f * g)); }
;     __device__ __forceinline__ void operator()(const f32x4 (&acc)[2][2][4][2], const Unit& u, int wr, int wc, int fr, int fq) const {
;         const int row0 = u.pm * BM + wr * 64 + fr, col0 = u.pn * 128 + wc * 32 + 8 * fq;
; #pragma unroll
;         for (int ai = 0; ai < 2; ++ai)
; #pragma unroll
;             for (int m = 0; m < 4; ++m) { if (m == 0) asm volatile("" ::: "memory"); const int row = row0 + ai * HALF + m * 16; const float rs = rstd_of(ssq, row);
;                 f32x4 o[2];
; #pragma unroll
;                 for (int n = 0; n < 2; ++n) { const f32x4 g = acc[ai][0][m][n] * rs, up = acc[ai][1][m][n] * rs;
; #pragma unroll
;                     for (int e = 0; e < 4; ++e) o[n][e] = g[e] * sigm(g[e]) * up[e]; }
;                 *(u32x4*)(O + (size_t)row * 2816 + col0) = pack8(o[0], o[1]); }
.LBB0_121:
	v_lshl_add_u32 v136, s0, 8, v140
	v_ashrrev_i32_e32 v137, 31, v136
	v_lshl_add_u64 v[144:145], v[136:137], 4, s[18:19]
	global_load_dwordx4 v[166:169], v[144:145], off offset:2048
	global_load_dwordx4 v[170:173], v[144:145], off offset:2304
	global_load_dwordx4 v[174:177], v[144:145], off offset:2560
	global_load_dwordx4 v[178:181], v[144:145], off offset:2816
	v_lshl_or_b32 v138, s1, 7, v142
	v_ashrrev_i32_e32 v139, 31, v138
	s_andn2_b64 vcc, exec, s[6:7]
	v_mov_b64_e32 v[144:145], v[222:223]
	v_mov_b64_e32 v[146:147], v[224:225]
	v_mov_b32_e32 v148, v145
	v_mov_b32_e32 v149, v146
	v_mov_b32_e32 v145, v147
	v_pk_add_f32 v[144:145], v[148:149], v[144:145]
	s_nop 0
	v_add_f32_e32 v137, v144, v145
	v_fmamk_f32 v137, v137, 0x3a800000, v231
	v_rsq_f32_e32 v144, v137
	v_mov_b32_e32 v191, v137
	v_mul_f32_e32 v190, 0xbfb8aa3b, v144
	v_mul_f32_e32 v182, v126, v190
	v_mul_f32_e32 v183, v127, v190
	v_mul_f32_e32 v184, v128, v190
	v_mul_f32_e32 v185, v129, v190
	v_mul_f32_e32 v186, v122, v190
	v_mul_f32_e32 v187, v123, v190
	v_mul_f32_e32 v188, v124, v190
	v_mul_f32_e32 v189, v125, v190
	v_exp_f32_e32 v182, v182
	v_exp_f32_e32 v183, v183
	v_exp_f32_e32 v184, v184
	v_exp_f32_e32 v185, v185
	v_exp_f32_e32 v186, v186
	v_exp_f32_e32 v187, v187
	v_exp_f32_e32 v188, v188
	v_exp_f32_e32 v189, v189
	v_fma_f32 v182, v182, v191, v191
	v_fma_f32 v183, v183, v191, v191
	v_fma_f32 v184, v184, v191, v191
	v_fma_f32 v185, v185, v191, v191
	v_fma_f32 v186, v186, v191, v191
	v_fma_f32 v187, v187, v191, v191
	v_fma_f32 v188, v188, v191, v191
	v_fma_f32 v189, v189, v191, v191
	v_rcp_f32_e32 v182, v182
	v_rcp_f32_e32 v183, v183
	v_rcp_f32_e32 v184, v184
	v_rcp_f32_e32 v185, v185
	v_rcp_f32_e32 v186, v186
	v_rcp_f32_e32 v187, v187
	v_rcp_f32_e32 v188, v188
	v_rcp_f32_e32 v189, v189
	v_pk_mul_f32 v[118:119], v[126:127], v[118:119]
	v_pk_mul_f32 v[120:121], v[128:129], v[120:121]
	v_pk_mul_f32 v[122:123], v[122:123], v[114:115]
	v_pk_mul_f32 v[124:125], v[124:125], v[116:117]
	v_pk_mul_f32 v[118:119], v[118:119], v[182:183]
	v_pk_mul_f32 v[120:121], v[120:121], v[184:185]
	v_pk_mul_f32 v[122:123], v[122:123], v[186:187]
	v_pk_mul_f32 v[124:125], v[124:125], v[188:189]
	v_cvt_pk_bf16_f32 v114, v118, v119
	v_mov_b64_e32 v[118:119], s[16:17]
	v_cvt_pk_bf16_f32 v115, v120, v121
	v_cvt_pk_bf16_f32 v116, v122, v123
	v_mad_i64_i32 v[122:123], s[0:1], v136, s92, v[118:119]
	v_lshlrev_b64 v[120:121], 1, v[138:139]
	v_cvt_pk_bf16_f32 v117, v124, v125
	v_lshl_add_u64 v[122:123], v[122:123], 0, v[120:121]
	global_store_dwordx4 v[122:123], v[114:117], off
	s_nop 1
	v_or_b32_e32 v114, 16, v136
	v_ashrrev_i32_e32 v115, 31, v114
	v_lshl_add_u64 v[116:117], v[114:115], 4, s[18:19]
	v_mov_b64_e32 v[122:123], v[226:227]
	v_mov_b64_e32 v[124:125], v[228:229]
	v_mov_b32_e32 v116, v123
	v_mov_b32_e32 v117, v124
	v_mov_b32_e32 v123, v125
	v_pk_add_f32 v[116:117], v[116:117], v[122:123]
	s_nop 0
	v_add_f32_e32 v115, v116, v117
	v_fmamk_f32 v115, v115, 0x3a800000, v231
	v_rsq_f32_e32 v116, v115
	v_mov_b32_e32 v191, v115
	v_mul_f32_e32 v190, 0xbfb8aa3b, v116
	v_mul_f32_e32 v182, v108, v190
	v_mul_f32_e32 v183, v109, v190
	v_mul_f32_e32 v184, v110, v190
	v_mul_f32_e32 v185, v111, v190
	v_mul_f32_e32 v186, v104, v190
	v_mul_f32_e32 v187, v105, v190
	v_mul_f32_e32 v188, v106, v190
	v_mul_f32_e32 v189, v107, v190
	v_exp_f32_e32 v182, v182
	v_exp_f32_e32 v183, v183
	v_exp_f32_e32 v184, v184
	v_exp_f32_e32 v185, v185
	v_exp_f32_e32 v186, v186
	v_exp_f32_e32 v187, v187
	v_exp_f32_e32 v188, v188
	v_exp_f32_e32 v189, v189
	v_fma_f32 v182, v182, v191, v191
	v_fma_f32 v183, v183, v191, v191
	v_fma_f32 v184, v184, v191, v191
	v_fma_f32 v185, v185, v191, v191
	v_fma_f32 v186, v186, v191, v191
	v_fma_f32 v187, v187, v191, v191
	v_fma_f32 v188, v188, v191, v191
	v_fma_f32 v189, v189, v191, v191
	v_rcp_f32_e32 v182, v182
	v_rcp_f32_e32 v183, v183
	v_rcp_f32_e32 v184, v184
	v_rcp_f32_e32 v185, v185
	v_rcp_f32_e32 v186, v186
	v_rcp_f32_e32 v187, v187
	v_rcp_f32_e32 v188, v188
	v_rcp_f32_e32 v189, v189
	v_pk_mul_f32 v[100:101], v[108:109], v[100:101]
	v_pk_mul_f32 v[102:103], v[110:111], v[102:103]
	v_pk_mul_f32 v[104:105], v[104:105], v[96:97]
	v_pk_mul_f32 v[106:107], v[106:107], v[98:99]
	v_pk_mul_f32 v[100:101], v[100:101], v[182:183]
	v_pk_mul_f32 v[102:103], v[102:103], v[184:185]
	v_pk_mul_f32 v[104:105], v[104:105], v[186:187]
	v_pk_mul_f32 v[106:107], v[106:107], v[188:189]
	v_cvt_pk_bf16_f32 v96, v100, v101
	v_mad_i64_i32 v[100:101], s[0:1], v114, s92, v[118:119]
	v_cvt_pk_bf16_f32 v97, v102, v103
	v_cvt_pk_bf16_f32 v98, v104, v105
	v_cvt_pk_bf16_f32 v99, v106, v107
	v_lshl_add_u64 v[100:101], v[100:101], 0, v[120:121]
	global_store_dwordx4 v[100:101], v[96:99], off
	s_nop 1
	v_or_b32_e32 v96, 32, v136
	v_ashrrev_i32_e32 v97, 31, v96
	v_lshl_add_u64 v[98:99], v[96:97], 4, s[18:19]
	v_mov_b64_e32 v[98:99], v[244:245]
	v_mov_b64_e32 v[100:101], v[246:247]
	v_mov_b32_e32 v102, v99
	v_mov_b32_e32 v103, v100
	v_mov_b32_e32 v99, v101
	v_pk_add_f32 v[98:99], v[102:103], v[98:99]
	s_nop 0
	v_add_f32_e32 v97, v98, v99
	v_fmamk_f32 v97, v97, 0x3a800000, v231
	v_rsq_f32_e32 v98, v97
	v_mov_b32_e32 v191, v97
	v_mul_f32_e32 v190, 0xbfb8aa3b, v98
	v_mul_f32_e32 v182, v92, v190
	v_mul_f32_e32 v183, v93, v190
	v_mul_f32_e32 v184, v94, v190
	v_mul_f32_e32 v185, v95, v190
	v_mul_f32_e32 v186, v88, v190
	v_mul_f32_e32 v187, v89, v190
	v_mul_f32_e32 v188, v90, v190
	v_mul_f32_e32 v189, v91, v190
	v_exp_f32_e32 v182, v182
	v_exp_f32_e32 v183, v183
	v_exp_f32_e32 v184, v184
	v_exp_f32_e32 v185, v185
	v_exp_f32_e32 v186, v186
	v_exp_f32_e32 v187, v187
	v_exp_f32_e32 v188, v188
	v_exp_f32_e32 v189, v189
; __device__ __forceinline__ u32x4 pack8(const f32x4 a, const f32x4 b) { u32x4 w; w.x = cvt_pk_bf16(a[0], a[1]); w.y = cvt_pk_bf16(a[2], a[3]); w.z = cvt_pk_bf16(b[0], b[1]); w.w = cvt_pk_bf16(b[2], b[3]); return w; }
; __device__ __forceinline__ float rstd_of(const float* ssq, int row) { const f32x4 a = *(const f32x4*)(ssq + (size_t)row * 4);
;     return __builtin_amdgcn_rsqf(((a[0] + a[1]) + (a[2] + a[3])) * (1.0f / 1024.0f) + 1e-6f); }
; __device__ __forceinline__ float sigm(float g) { return __builtin_amdgcn_rcpf(1.0f + __builtin_amdgcn_exp2f(-1.4426950408889634f * g)); }
;     __device__ __forceinline__ void operator()(const f32x4 (&acc)[2][2][4][2], const Unit& u, int wr, int wc, int fr, int fq) const {
;         const int row0 = u.pm * BM + wr * 64 + fr, col0 = u.pn * 128 + wc * 32 + 8 * fq;
; #pragma unroll
;         for (int ai = 0; ai < 2; ++ai)
; #pragma unroll
;             for (int m = 0; m < 4; ++m) { if (m == 0) asm volatile("" ::: "memory"); const int row = row0 + ai * HALF + m * 16; const float rs = rstd_of(ssq, row);
;                 f32x4 o[2];
; #pragma unroll
;                 for (int n = 0; n < 2; ++n) { const f32x4 g = acc[ai][0][m][n] * rs, up = acc[ai][1][m][n] * rs;
; #pragma unroll
;                     for (int e = 0; e < 4; ++e) o[n][e] = g[e] * sigm(g[e]) * up[e]; }
;                 *(u32x4*)(O + (size_t)row * 2816 + col0) = pack8(o[0], o[1]); }
	v_fma_f32 v182, v182, v191, v191
	v_fma_f32 v183, v183, v191, v191
	v_fma_f32 v184, v184, v191, v191
	v_fma_f32 v185, v185, v191, v191
	v_fma_f32 v186, v186, v191, v191
	v_fma_f32 v187, v187, v191, v191
	v_fma_f32 v188, v188, v191, v191
	v_fma_f32 v189, v189, v191, v191
	v_rcp_f32_e32 v182, v182
	v_rcp_f32_e32 v183, v183
	v_rcp_f32_e32 v184, v184
	v_rcp_f32_e32 v185, v185
	v_rcp_f32_e32 v186, v186
	v_rcp_f32_e32 v187, v187
	v_rcp_f32_e32 v188, v188
	v_rcp_f32_e32 v189, v189
	v_pk_mul_f32 v[84:85], v[92:93], v[84:85]
	v_pk_mul_f32 v[86:87], v[94:95], v[86:87]
	v_pk_mul_f32 v[88:89], v[88:89], v[80:81]
	v_pk_mul_f32 v[90:91], v[90:91], v[82:83]
	v_pk_mul_f32 v[84:85], v[84:85], v[182:183]
	v_pk_mul_f32 v[86:87], v[86:87], v[184:185]
	v_pk_mul_f32 v[88:89], v[88:89], v[186:187]
	v_pk_mul_f32 v[90:91], v[90:91], v[188:189]
	v_cvt_pk_bf16_f32 v80, v84, v85
	v_mad_i64_i32 v[84:85], s[0:1], v96, s92, v[118:119]
	v_cvt_pk_bf16_f32 v81, v86, v87
	v_cvt_pk_bf16_f32 v82, v88, v89
	v_cvt_pk_bf16_f32 v83, v90, v91
	v_lshl_add_u64 v[84:85], v[84:85], 0, v[120:121]
	global_store_dwordx4 v[84:85], v[80:83], off
	s_nop 1
	v_or_b32_e32 v80, 48, v136
	v_ashrrev_i32_e32 v81, 31, v80
	v_lshl_add_u64 v[82:83], v[80:81], 4, s[18:19]
	v_mov_b64_e32 v[82:83], v[248:249]
	v_mov_b64_e32 v[84:85], v[250:251]
	v_mov_b32_e32 v86, v83
	v_mov_b32_e32 v87, v84
	v_mov_b32_e32 v83, v85
	v_pk_add_f32 v[82:83], v[86:87], v[82:83]
	s_nop 0
	v_add_f32_e32 v81, v82, v83
	v_fmamk_f32 v81, v81, 0x3a800000, v231
	v_rsq_f32_e32 v82, v81
	v_mov_b32_e32 v191, v81
	v_mul_f32_e32 v190, 0xbfb8aa3b, v82
	v_mul_f32_e32 v182, v76, v190
	v_mul_f32_e32 v183, v77, v190
	v_mul_f32_e32 v184, v78, v190
	v_mul_f32_e32 v185, v79, v190
	v_mul_f32_e32 v186, v72, v190
	v_mul_f32_e32 v187, v73, v190
	v_mul_f32_e32 v188, v74, v190
	v_mul_f32_e32 v189, v75, v190
	v_exp_f32_e32 v182, v182
	v_exp_f32_e32 v183, v183
	v_exp_f32_e32 v184, v184
	v_exp_f32_e32 v185, v185
	v_exp_f32_e32 v186, v186
	v_exp_f32_e32 v187, v187
	v_exp_f32_e32 v188, v188
	v_exp_f32_e32 v189, v189
	v_fma_f32 v182, v182, v191, v191
	v_fma_f32 v183, v183, v191, v191
	v_fma_f32 v184, v184, v191, v191
	v_fma_f32 v185, v185, v191, v191
	v_fma_f32 v186, v186, v191, v191
	v_fma_f32 v187, v187, v191, v191
	v_fma_f32 v188, v188, v191, v191
	v_fma_f32 v189, v189, v191, v191
	v_rcp_f32_e32 v182, v182
	v_rcp_f32_e32 v183, v183
	v_rcp_f32_e32 v184, v184
	v_rcp_f32_e32 v185, v185
	v_rcp_f32_e32 v186, v186
	v_rcp_f32_e32 v187, v187
	v_rcp_f32_e32 v188, v188
	v_rcp_f32_e32 v189, v189
	v_pk_mul_f32 v[68:69], v[76:77], v[68:69]
	v_pk_mul_f32 v[70:71], v[78:79], v[70:71]
	v_pk_mul_f32 v[72:73], v[72:73], v[64:65]
	v_pk_mul_f32 v[74:75], v[74:75], v[66:67]
	v_pk_mul_f32 v[68:69], v[68:69], v[182:183]
	v_pk_mul_f32 v[70:71], v[70:71], v[184:185]
	v_pk_mul_f32 v[72:73], v[72:73], v[186:187]
	v_pk_mul_f32 v[74:75], v[74:75], v[188:189]
	v_cvt_pk_bf16_f32 v64, v68, v69
	v_mad_i64_i32 v[68:69], s[0:1], v80, s92, v[118:119]
	v_cvt_pk_bf16_f32 v65, v70, v71
	v_cvt_pk_bf16_f32 v66, v72, v73
	v_cvt_pk_bf16_f32 v67, v74, v75
	v_lshl_add_u64 v[68:69], v[68:69], 0, v[120:121]
	global_store_dwordx4 v[68:69], v[64:67], off
	s_nop 1
	v_add_u32_e32 v64, 0x80, v136
	v_ashrrev_i32_e32 v65, 31, v64
	v_lshl_add_u64 v[66:67], v[64:65], 4, s[18:19]
	s_waitcnt vmcnt(7)
	v_mov_b64_e32 v[66:67], v[166:167]
	v_mov_b64_e32 v[68:69], v[168:169]
	v_mov_b32_e32 v70, v67
	v_mov_b32_e32 v71, v68
	v_mov_b32_e32 v67, v69
	v_pk_add_f32 v[66:67], v[70:71], v[66:67]
	s_nop 0
	v_add_f32_e32 v65, v66, v67
	v_fmamk_f32 v65, v65, 0x3a800000, v231
	v_rsq_f32_e32 v66, v65
	v_mov_b32_e32 v191, v65
	v_mul_f32_e32 v190, 0xbfb8aa3b, v66
	v_mul_f32_e32 v182, v60, v190
	v_mul_f32_e32 v183, v61, v190
	v_mul_f32_e32 v184, v62, v190
	v_mul_f32_e32 v185, v63, v190
	v_mul_f32_e32 v186, v56, v190
	v_mul_f32_e32 v187, v57, v190
	v_mul_f32_e32 v188, v58, v190
	v_mul_f32_e32 v189, v59, v190
	v_exp_f32_e32 v182, v182
	v_exp_f32_e32 v183, v183
	v_exp_f32_e32 v184, v184
	v_exp_f32_e32 v185, v185
	v_exp_f32_e32 v186, v186
	v_exp_f32_e32 v187, v187
	v_exp_f32_e32 v188, v188
	v_exp_f32_e32 v189, v189
	v_fma_f32 v182, v182, v191, v191
	v_fma_f32 v183, v183, v191, v191
	v_fma_f32 v184, v184, v191, v191
	v_fma_f32 v185, v185, v191, v191
	v_fma_f32 v186, v186, v191, v191
	v_fma_f32 v187, v187, v191, v191
	v_fma_f32 v188, v188, v191, v191
	v_fma_f32 v189, v189, v191, v191
	v_rcp_f32_e32 v182, v182
	v_rcp_f32_e32 v183, v183
	v_rcp_f32_e32 v184, v184
	v_rcp_f32_e32 v185, v185
	v_rcp_f32_e32 v186, v186
	v_rcp_f32_e32 v187, v187
	v_rcp_f32_e32 v188, v188
	v_rcp_f32_e32 v189, v189
	v_pk_mul_f32 v[52:53], v[60:61], v[52:53]
	v_pk_mul_f32 v[54:55], v[62:63], v[54:55]
	v_pk_mul_f32 v[56:57], v[56:57], v[48:49]
	v_pk_mul_f32 v[58:59], v[58:59], v[50:51]
	v_pk_mul_f32 v[52:53], v[52:53], v[182:183]
	v_pk_mul_f32 v[54:55], v[54:55], v[184:185]
	v_pk_mul_f32 v[56:57], v[56:57], v[186:187]
	v_pk_mul_f32 v[58:59], v[58:59], v[188:189]
	v_cvt_pk_bf16_f32 v48, v52, v53
	v_mad_i64_i32 v[52:53], s[0:1], v64, s92, v[118:119]
	v_cvt_pk_bf16_f32 v49, v54, v55
	v_cvt_pk_bf16_f32 v50, v56, v57
	v_cvt_pk_bf16_f32 v51, v58, v59
	v_lshl_add_u64 v[52:53], v[52:53], 0, v[120:121]
	global_store_dwordx4 v[52:53], v[48:51], off
	s_nop 1
	v_add_u32_e32 v48, 0x90, v136
	v_ashrrev_i32_e32 v49, 31, v48
	v_lshl_add_u64 v[50:51], v[48:49], 4, s[18:19]
	s_waitcnt vmcnt(7)
; __device__ __forceinline__ u32x4 pack8(const f32x4 a, const f32x4 b) { u32x4 w; w.x = cvt_pk_bf16(a[0], a[1]); w.y = cvt_pk_bf16(a[2], a[3]); w.z = cvt_pk_bf16(b[0], b[1]); w.w = cvt_pk_bf16(b[2], b[3]); return w; }
; __device__ __forceinline__ float sigm(float g) { return __builtin_amdgcn_rcpf(1.0f + __builtin_amdgcn_exp2f(-1.4426950408889634f * g)); }
; #define PG8_BAR __builtin_amdgcn_s_barrier()
;     __device__ __forceinline__ void operator()(const f32x4 (&acc)[2][2][4][2], const Unit& u, int wr, int wc, int fr, int fq) const {
;         const int row0 = u.pm * BM + wr * 64 + fr, col0 = u.pn * 128 + wc * 32 + 8 * fq;
; #pragma unroll
;         for (int ai = 0; ai < 2; ++ai)
; #pragma unroll
;             for (int m = 0; m < 4; ++m) { if (m == 0) asm volatile("" ::: "memory"); const int row = row0 + ai * HALF + m * 16; const float rs = rstd_of(ssq, row);
;                 f32x4 o[2];
; #pragma unroll
;                 for (int n = 0; n < 2; ++n) { const f32x4 g = acc[ai][0][m][n] * rs, up = acc[ai][1][m][n] * rs;
; #pragma unroll
;                     for (int e = 0; e < 4; ++e) o[n][e] = g[e] * sigm(g[e]) * up[e]; }
;                 *(u32x4*)(O + (size_t)row * 2816 + col0) = pack8(o[0], o[1]); }
; template <class Epi, class Sched, bool ALIGN_EPI = false, bool SP2 = false>
; __device__ __forceinline__ void gemm_phase(PG8_LAS unsigned char* lds, const Gemm g, const Sched& S, const Epi& E) {
;     ...
;         if constexpr (!Epi::AFTER_DRAIN) { E(acc, cur, wr, wc, fr, fq); S.done(cur); }
;         if (!has_next) break;
; #pragma unroll
;         for (int a = 0; a < 2; ++a)
; #pragma unroll
;             for (int b = 0; b < 2; ++b)
; #pragma unroll
;                 for (int m = 0; m < 4; ++m)
; #pragma unroll
;                     for (int n = 0; n < 2; ++n) acc[a][b][m][n] = (f32x4){0.f, 0.f, 0.f, 0.f};
;         cur = nxt; cA = nA; cB = nB; ++ui;
;         if constexpr (ALIGN_EPI) { if (wr == 1) PG8_BAR; }
	v_mov_b64_e32 v[50:51], v[170:171]
	v_mov_b64_e32 v[52:53], v[172:173]
	v_mov_b32_e32 v54, v51
	v_mov_b32_e32 v55, v52
	v_mov_b32_e32 v51, v53
	v_pk_add_f32 v[50:51], v[54:55], v[50:51]
	s_nop 0
	v_add_f32_e32 v49, v50, v51
	v_fmamk_f32 v49, v49, 0x3a800000, v231
	v_rsq_f32_e32 v50, v49
	v_mov_b32_e32 v191, v49
	v_mul_f32_e32 v190, 0xbfb8aa3b, v50
	v_mul_f32_e32 v182, v44, v190
	v_mul_f32_e32 v183, v45, v190
	v_mul_f32_e32 v184, v46, v190
	v_mul_f32_e32 v185, v47, v190
	v_mul_f32_e32 v186, v40, v190
	v_mul_f32_e32 v187, v41, v190
	v_mul_f32_e32 v188, v42, v190
	v_mul_f32_e32 v189, v43, v190
	v_exp_f32_e32 v182, v182
	v_exp_f32_e32 v183, v183
	v_exp_f32_e32 v184, v184
	v_exp_f32_e32 v185, v185
	v_exp_f32_e32 v186, v186
	v_exp_f32_e32 v187, v187
	v_exp_f32_e32 v188, v188
	v_exp_f32_e32 v189, v189
	v_fma_f32 v182, v182, v191, v191
	v_fma_f32 v183, v183, v191, v191
	v_fma_f32 v184, v184, v191, v191
	v_fma_f32 v185, v185, v191, v191
	v_fma_f32 v186, v186, v191, v191
	v_fma_f32 v187, v187, v191, v191
	v_fma_f32 v188, v188, v191, v191
	v_fma_f32 v189, v189, v191, v191
	v_rcp_f32_e32 v182, v182
	v_rcp_f32_e32 v183, v183
	v_rcp_f32_e32 v184, v184
	v_rcp_f32_e32 v185, v185
	v_rcp_f32_e32 v186, v186
	v_rcp_f32_e32 v187, v187
	v_rcp_f32_e32 v188, v188
	v_rcp_f32_e32 v189, v189
	v_pk_mul_f32 v[36:37], v[44:45], v[36:37]
	v_pk_mul_f32 v[38:39], v[46:47], v[38:39]
	v_pk_mul_f32 v[40:41], v[40:41], v[32:33]
	v_pk_mul_f32 v[42:43], v[42:43], v[34:35]
	v_pk_mul_f32 v[36:37], v[36:37], v[182:183]
	v_pk_mul_f32 v[38:39], v[38:39], v[184:185]
	v_pk_mul_f32 v[40:41], v[40:41], v[186:187]
	v_pk_mul_f32 v[42:43], v[42:43], v[188:189]
	v_cvt_pk_bf16_f32 v32, v36, v37
	v_mad_i64_i32 v[36:37], s[0:1], v48, s92, v[118:119]
	v_cvt_pk_bf16_f32 v33, v38, v39
	v_cvt_pk_bf16_f32 v34, v40, v41
	v_cvt_pk_bf16_f32 v35, v42, v43
	v_lshl_add_u64 v[36:37], v[36:37], 0, v[120:121]
	global_store_dwordx4 v[36:37], v[32:35], off
	s_nop 1
	v_add_u32_e32 v32, 0xa0, v136
	v_ashrrev_i32_e32 v33, 31, v32
	v_lshl_add_u64 v[34:35], v[32:33], 4, s[18:19]
	s_waitcnt vmcnt(7)
	v_mov_b64_e32 v[34:35], v[174:175]
	v_mov_b64_e32 v[36:37], v[176:177]
	v_mov_b32_e32 v38, v35
	v_mov_b32_e32 v39, v36
	v_mov_b32_e32 v35, v37
	v_pk_add_f32 v[34:35], v[38:39], v[34:35]
	s_nop 0
	v_add_f32_e32 v33, v34, v35
	v_fmamk_f32 v33, v33, 0x3a800000, v231
	v_rsq_f32_e32 v34, v33
	v_mov_b32_e32 v191, v33
	v_mul_f32_e32 v190, 0xbfb8aa3b, v34
	v_mul_f32_e32 v182, v28, v190
	v_mul_f32_e32 v183, v29, v190
	v_mul_f32_e32 v184, v30, v190
	v_mul_f32_e32 v185, v31, v190
	v_mul_f32_e32 v186, v24, v190
	v_mul_f32_e32 v187, v25, v190
	v_mul_f32_e32 v188, v26, v190
	v_mul_f32_e32 v189, v27, v190
	v_exp_f32_e32 v182, v182
	v_exp_f32_e32 v183, v183
	v_exp_f32_e32 v184, v184
	v_exp_f32_e32 v185, v185
	v_exp_f32_e32 v186, v186
	v_exp_f32_e32 v187, v187
	v_exp_f32_e32 v188, v188
	v_exp_f32_e32 v189, v189
	v_fma_f32 v182, v182, v191, v191
	v_fma_f32 v183, v183, v191, v191
	v_fma_f32 v184, v184, v191, v191
	v_fma_f32 v185, v185, v191, v191
	v_fma_f32 v186, v186, v191, v191
	v_fma_f32 v187, v187, v191, v191
	v_fma_f32 v188, v188, v191, v191
	v_fma_f32 v189, v189, v191, v191
	v_rcp_f32_e32 v182, v182
	v_rcp_f32_e32 v183, v183
	v_rcp_f32_e32 v184, v184
	v_rcp_f32_e32 v185, v185
	v_rcp_f32_e32 v186, v186
	v_rcp_f32_e32 v187, v187
	v_rcp_f32_e32 v188, v188
	v_rcp_f32_e32 v189, v189
	v_pk_mul_f32 v[20:21], v[28:29], v[20:21]
	v_pk_mul_f32 v[22:23], v[30:31], v[22:23]
	v_pk_mul_f32 v[24:25], v[24:25], v[16:17]
	v_pk_mul_f32 v[26:27], v[26:27], v[18:19]
	v_pk_mul_f32 v[20:21], v[20:21], v[182:183]
	v_pk_mul_f32 v[22:23], v[22:23], v[184:185]
	v_pk_mul_f32 v[24:25], v[24:25], v[186:187]
	v_pk_mul_f32 v[26:27], v[26:27], v[188:189]
	v_cvt_pk_bf16_f32 v16, v20, v21
	v_mad_i64_i32 v[20:21], s[0:1], v32, s92, v[118:119]
	v_cvt_pk_bf16_f32 v17, v22, v23
	v_cvt_pk_bf16_f32 v18, v24, v25
	v_cvt_pk_bf16_f32 v19, v26, v27
	v_lshl_add_u64 v[20:21], v[20:21], 0, v[120:121]
	global_store_dwordx4 v[20:21], v[16:19], off
	s_nop 1
	v_add_u32_e32 v16, 0xb0, v136
	v_ashrrev_i32_e32 v17, 31, v16
	v_lshl_add_u64 v[18:19], v[16:17], 4, s[18:19]
	s_waitcnt vmcnt(7)
	v_mov_b64_e32 v[18:19], v[178:179]
	v_mov_b64_e32 v[20:21], v[180:181]
	v_mov_b32_e32 v22, v19
	v_mov_b32_e32 v23, v20
	v_mov_b32_e32 v19, v21
	v_pk_add_f32 v[18:19], v[22:23], v[18:19]
	s_nop 0
	v_add_f32_e32 v17, v18, v19
	v_fmamk_f32 v17, v17, 0x3a800000, v231
	v_rsq_f32_e32 v18, v17
	v_mov_b32_e32 v191, v17
	v_mul_f32_e32 v190, 0xbfb8aa3b, v18
	v_mul_f32_e32 v182, v12, v190
	v_mul_f32_e32 v183, v13, v190
	v_mul_f32_e32 v184, v14, v190
	v_mul_f32_e32 v185, v15, v190
	v_mul_f32_e32 v186, v8, v190
	v_mul_f32_e32 v187, v9, v190
	v_mul_f32_e32 v188, v10, v190
	v_mul_f32_e32 v189, v11, v190
	v_exp_f32_e32 v182, v182
	v_exp_f32_e32 v183, v183
	v_exp_f32_e32 v184, v184
	v_exp_f32_e32 v185, v185
	v_exp_f32_e32 v186, v186
	v_exp_f32_e32 v187, v187
	v_exp_f32_e32 v188, v188
	v_exp_f32_e32 v189, v189
	v_fma_f32 v182, v182, v191, v191
	v_fma_f32 v183, v183, v191, v191
	v_fma_f32 v184, v184, v191, v191
	v_fma_f32 v185, v185, v191, v191
	v_fma_f32 v186, v186, v191, v191
	v_fma_f32 v187, v187, v191, v191
	v_fma_f32 v188, v188, v191, v191
	v_fma_f32 v189, v189, v191, v191
	v_rcp_f32_e32 v182, v182
	v_rcp_f32_e32 v183, v183
	v_rcp_f32_e32 v184, v184
	v_rcp_f32_e32 v185, v185
	v_rcp_f32_e32 v186, v186
	v_rcp_f32_e32 v187, v187
	v_rcp_f32_e32 v188, v188
	v_rcp_f32_e32 v189, v189
	v_pk_mul_f32 v[4:5], v[12:13], v[4:5]
	v_pk_mul_f32 v[6:7], v[14:15], v[6:7]
	v_pk_mul_f32 v[8:9], v[8:9], v[0:1]
	v_pk_mul_f32 v[10:11], v[10:11], v[2:3]
	v_pk_mul_f32 v[4:5], v[4:5], v[182:183]
	v_pk_mul_f32 v[6:7], v[6:7], v[184:185]
	v_pk_mul_f32 v[8:9], v[8:9], v[186:187]
	v_pk_mul_f32 v[10:11], v[10:11], v[188:189]
	v_cvt_pk_bf16_f32 v0, v4, v5
	v_mad_i64_i32 v[4:5], s[0:1], v16, s92, v[118:119]
	v_cvt_pk_bf16_f32 v1, v6, v7
	v_cvt_pk_bf16_f32 v2, v8, v9
	v_cvt_pk_bf16_f32 v3, v10, v11
	v_lshl_add_u64 v[4:5], v[4:5], 0, v[120:121]
	s_mov_b64 s[0:1], -1
	global_store_dwordx4 v[4:5], v[0:3], off
	s_cbranch_vccnz .LBB0_114
	s_andn2_b64 vcc, exec, s[10:11]
	s_cbranch_vccnz .LBB0_113
	s_barrier
	s_branch .LBB0_113
